# gdn chain loader prologue: the 25 pacing sleeps before the first step removed (nothing to protect before the compute waves start)
# speedup vs baseline: 1.0079x; 1.0011x over previous
; #define LBAR() do { asm volatile("s_waitcnt lgkmcnt(0)" ::: "memory"); __builtin_amdgcn_s_barrier(); asm volatile("" ::: "memory"); } while (0)
; #define WAITV(N_) asm volatile("s_waitcnt vmcnt(" #N_ ")" ::: "memory")
; #define ISSUE_XG(s_) do { const unsigned char* g_ = A.blob + (unit0 + CHUNK_OF(s_)) * BLOB + lane * 16; const unsigned l_ = lds0 + ((s_) & 1) * C_BUF; \
;         _Pragma("unroll") for (int k = 0; k < 8; ++k) { const unsigned o_ = (lw + 4 * k) * 1024; DMA1(g_ + o_, l_ + o_); __builtin_amdgcn_s_sleep(LOADER_PACE); } } while (0)
; #define WAITV(N_) asm volatile("s_waitcnt vmcnt(" #N_ ")" ::: "memory")
; #define ISSUE_XG(s_) do { const unsigned char* g_ = A.blobA + (unit0 + CHUNK_OF(s_)) * BLOBA + qo + lane * 16; const unsigned l_ = lds0 + ((s_) & 1) * CB_BUF; \
;         _Pragma("unroll") for (int k = 0; k < 4; ++k) { const unsigned o_ = (lw + 4 * k) * 1024; DMA1(g_ + o_, l_ + o_); } } while (0)
; __device__ __forceinline__ void gdn_chain_unit(LAS unsigned char* lds, const GdnChainArgs& A, int item, int half) {
;     ...
;     if (w >= 4) {
;         const unsigned tbo = c ? B_TBB : B_TBF;
;     ...
;         if (!(flags & 4)) { ISSUE_XG(0); ISSUE_YG(0); ISSUE_XG(1); }
;         WAITV(0);
;         LBAR();
.LBB0_655:
	s_and_b64 vcc, exec, s[2:3]
	s_cbranch_vccz .LBB0_667
	v_readlane_b32 s2, v253, 53
	v_readlane_b32 s3, v253, 54
	s_lshl_b32 s34, s62, 10
	s_or_b32 s4, s34, 0x1000
	v_lshl_add_u64 v[2:3], s[2:3], 0, v[130:131]
	s_add_i32 s2, s34, 0
	v_lshl_add_u64 v[4:5], v[2:3], 0, s[34:35]
	s_mov_b32 m0, s2
	s_nop 0
	global_load_lds_dwordx4 v[4:5], off
	s_mov_b32 s5, s35
	s_add_i32 s2, s4, 0
	s_or_b32 s6, s34, 0x2000
	s_nop 0
	v_lshl_add_u64 v[4:5], v[2:3], 0, s[4:5]
	s_mov_b32 m0, s2
	s_nop 0
	global_load_lds_dwordx4 v[4:5], off
	s_mov_b32 s7, s35
	s_add_i32 s2, s6, 0
	s_or_b32 s36, s34, 0x3000
	s_nop 0
	v_lshl_add_u64 v[4:5], v[2:3], 0, s[6:7]
	s_mov_b32 m0, s2
	s_nop 0
	global_load_lds_dwordx4 v[4:5], off
	s_mov_b32 s37, s35
	s_add_i32 s2, s36, 0
	s_or_b32 s38, s34, 0x4000
	s_nop 0
	v_lshl_add_u64 v[4:5], v[2:3], 0, s[36:37]
	s_mov_b32 m0, s2
	s_nop 0
	global_load_lds_dwordx4 v[4:5], off
	s_mov_b32 s39, s35
	s_add_i32 s2, s38, 0
	s_or_b32 s40, s34, 0x5000
	s_nop 0
	v_lshl_add_u64 v[4:5], v[2:3], 0, s[38:39]
	s_mov_b32 m0, s2
	s_nop 0
	global_load_lds_dwordx4 v[4:5], off
	s_mov_b32 s41, s35
	s_add_i32 s2, s40, 0
	s_or_b32 s42, s34, 0x6000
	s_nop 0
	v_lshl_add_u64 v[4:5], v[2:3], 0, s[40:41]
	s_mov_b32 m0, s2
	s_nop 0
	global_load_lds_dwordx4 v[4:5], off
	s_mov_b32 s43, s35
	s_add_i32 s2, s42, 0
	s_or_b32 s44, s34, 0x7000
	s_nop 0
	v_lshl_add_u64 v[4:5], v[2:3], 0, s[42:43]
	s_mov_b32 m0, s2
	s_nop 0
	global_load_lds_dwordx4 v[4:5], off
	s_mov_b32 s45, s35
	s_add_i32 s2, s44, 0
	s_or_b32 s46, s34, 0x8000
	s_nop 0
	v_lshl_add_u64 v[4:5], v[2:3], 0, s[44:45]
	s_mov_b32 m0, s2
	s_nop 0
	global_load_lds_dwordx4 v[4:5], off
	s_mov_b32 s47, s35
	s_add_i32 s2, s46, 0
	s_or_b32 s48, s34, 0x9000
	s_nop 0
	v_lshl_add_u64 v[4:5], v[2:3], 0, s[46:47]
	s_mov_b32 m0, s2
	s_nop 0
	global_load_lds_dwordx4 v[4:5], off
	s_mov_b32 s49, s35
	s_add_i32 s2, s48, 0
	s_or_b32 s50, s34, 0xa000
	s_nop 0
	v_lshl_add_u64 v[4:5], v[2:3], 0, s[48:49]
	s_mov_b32 m0, s2
	s_nop 0
	global_load_lds_dwordx4 v[4:5], off
	s_mov_b32 s51, s35
	s_add_i32 s2, s50, 0
	s_or_b32 s52, s34, 0xb000
	s_nop 0
	v_lshl_add_u64 v[4:5], v[2:3], 0, s[50:51]
	s_mov_b32 m0, s2
	s_nop 0
	global_load_lds_dwordx4 v[4:5], off
	s_mov_b32 s53, s35
	s_add_i32 s2, s52, 0
	s_nop 0
	v_lshl_add_u64 v[4:5], v[2:3], 0, s[52:53]
	s_mov_b32 m0, s2
	s_nop 0
	global_load_lds_dwordx4 v[4:5], off
	s_or_b32 s2, s62, 16
	s_lshl_b32 s3, s2, 10
	v_readlane_b32 s54, v253, 61
	s_or_b32 s67, s3, 0x8000
	s_add_i32 s3, s3, s54
	s_cmp_lt_u32 s2, 18
	s_cselect_b32 s54, s67, s3
	s_mov_b32 s55, s35
	s_add_i32 s2, s67, 0
	s_nop 0
	v_lshl_add_u64 v[4:5], v[2:3], 0, s[54:55]
	s_mov_b32 m0, s2
	s_nop 0
	global_load_lds_dwordx4 v[4:5], off
	s_or_b32 s72, s34, 0xd000
	v_readlane_b32 s2, v253, 59
	s_or_b32 s56, s2, s34
	s_mov_b32 s57, s35
	s_add_i32 s2, s72, 0
	s_nop 0
	v_lshl_add_u64 v[4:5], v[2:3], 0, s[56:57]
	s_mov_b32 m0, s2
	s_nop 0
	global_load_lds_dwordx4 v[4:5], off
	s_or_b32 s73, s34, 0xe000
	v_readlane_b32 s2, v253, 60
	s_or_b32 s58, s2, s34
	s_mov_b32 s59, s35
	s_add_i32 s2, s73, 0
	s_nop 0
	v_lshl_add_u64 v[4:5], v[2:3], 0, s[58:59]
	s_mov_b32 m0, s2
	s_nop 0
	global_load_lds_dwordx4 v[4:5], off
	s_or_b32 s74, s34, 0xf000
	v_readlane_b32 s2, v253, 62
	s_or_b32 s60, s2, s34
	s_mov_b32 s61, s35
	s_add_i32 s2, s74, 0
	s_nop 0
	v_lshl_add_u64 v[4:5], v[2:3], 0, s[60:61]
	s_mov_b32 m0, s2
	s_nop 0
	global_load_lds_dwordx4 v[4:5], off
	s_or_b32 s2, s62, 32
	s_cmp_lt_u32 s2, 34
	s_cselect_b64 s[64:65], -1, 0
	s_lshl_b32 s75, s2, 10
	s_mov_b64 s[2:3], -1
	s_and_b64 vcc, exec, s[64:65]
	s_nop 0
	s_cbranch_vccnz .LBB0_658
	v_readlane_b32 s2, v253, 61
	s_add_i32 s62, s75, s2
	s_mov_b32 s63, s35
	s_mov_b64 s[2:3], 0
.LBB0_658:
	s_mov_b64 s[70:71], s[94:95]
	s_andn2_b64 vcc, exec, s[2:3]
	s_cbranch_vccnz .LBB0_660
	v_readlane_b32 s3, v253, 61
	s_add_i32 s2, s75, 0
	s_add_i32 s62, s75, s3
	s_mov_b32 s63, s35
	s_add_i32 s2, s2, 0x8000
	v_lshl_add_u64 v[2:3], v[2:3], 0, s[62:63]
	s_mov_b32 m0, s2
	s_nop 0
	global_load_lds_dwordx4 v[2:3], off
	s_nop 0
.LBB0_660:
	v_readlane_b32 s2, v252, 1
	v_readlane_b32 s3, v252, 2
	s_add_i32 s76, 0, 0x10800
	v_readlane_b32 vcc_lo, v254, 44
	v_lshl_add_u64 v[2:3], s[2:3], 0, v[130:131]
	s_add_i32 s2, s34, s76
	v_lshl_add_u64 v[4:5], v[2:3], 0, s[34:35]
	s_mov_b32 m0, s2
	s_nop 0
	global_load_lds_dwordx4 v[4:5], off
	s_add_i32 s2, s4, s76
	s_nop 0
	v_lshl_add_u64 v[4:5], v[2:3], 0, s[4:5]
	s_mov_b32 m0, s2
	s_nop 0
	global_load_lds_dwordx4 v[4:5], off
	s_add_i32 s2, s6, s76
	s_nop 0
	v_lshl_add_u64 v[4:5], v[2:3], 0, s[6:7]
	s_mov_b32 m0, s2
	s_nop 0
	global_load_lds_dwordx4 v[4:5], off
	s_add_i32 s2, s36, s76
	s_nop 0
	v_lshl_add_u64 v[4:5], v[2:3], 0, s[36:37]
	s_mov_b32 m0, s2
	s_nop 0
	global_load_lds_dwordx4 v[4:5], off
	s_add_i32 s2, s38, s76
	s_nop 0
	v_lshl_add_u64 v[4:5], v[2:3], 0, s[38:39]
	s_mov_b32 m0, s2
	s_nop 0
	global_load_lds_dwordx4 v[4:5], off
	s_add_i32 s2, s40, s76
	s_nop 0
	v_lshl_add_u64 v[4:5], v[2:3], 0, s[40:41]
	s_mov_b32 m0, s2
	s_nop 0
	global_load_lds_dwordx4 v[4:5], off
	s_add_i32 s2, s42, s76
	s_nop 0
	v_lshl_add_u64 v[4:5], v[2:3], 0, s[42:43]
	s_mov_b32 m0, s2
	s_nop 0
	global_load_lds_dwordx4 v[4:5], off
	s_nop 0
	v_lshl_add_u64 v[2:3], v[2:3], 0, s[44:45]
	s_add_i32 s2, s44, s76
	s_mov_b32 m0, s2
	s_nop 0
	global_load_lds_dwordx4 v[2:3], off
	s_nop 0
	s_waitcnt vmcnt(0)
	s_waitcnt lgkmcnt(0)
	s_barrier
	v_readlane_b32 s2, v253, 63
	v_readlane_b32 s3, v252, 0
	v_readlane_b32 s94, v254, 46
	s_add_i32 s77, s75, 0x8000
	v_lshl_add_u64 v[2:3], s[2:3], 0, v[130:131]
	s_mov_b32 s80, 0
	s_mov_b32 s78, 30
	v_readlane_b32 vcc_hi, v254, 45
	v_readlane_b32 s95, v254, 47
	s_branch .LBB0_662
